# attention phase: weight-conversion (TR) units are claimed before the attention work queues instead of after, so the phase tail ends on short attention units
# baseline (speedup 1.0000x reference)
; #define LAS __attribute__((address_space(3)))
; __device__ __forceinline__ KArgP kargs() { KArgP p = (KArgP)__builtin_amdgcn_kernarg_segment_ptr(); asm volatile("" : "+s"(p)); return p; }
; __global__ void __launch_bounds__(NWAVES * 64) fwd_kernel(Args args) {
;     extern __shared__ __attribute__((aligned(16))) unsigned char lds[];
;     cg::grid_group grid = cg::this_grid();
;     { volatile LAS unsigned* m0 = (volatile LAS unsigned*)((LAS unsigned char*)lds + att::OFF_MISC); if (threadIdx.x < 16) m0[threadIdx.x] = 0u; }
;     __syncthreads();
;     XcdBarrier bar = xcd_barrier_post((unsigned*)(kargs()->ws + WS_CTL) + CW_BAR, (volatile LAS unsigned*)((LAS unsigned char*)lds + att::OFF_MISC) + 8);
_Z10fwd_kernel4Args:
	s_mov_b64 s[68:69], s[0:1]
	s_mov_b32 s98, 0
	s_load_dwordx4 s[72:75], s[0:1], 0x98
	s_add_u32 s0, s68, 0xa0
	s_addc_u32 s1, s69, 0
	v_and_b32_e32 v214, 0x3ff, v0
	v_writelane_b32 v253, s0, 0
	s_mov_b32 s67, s2
	v_cmp_gt_u32_e32 vcc, 16, v214
	v_writelane_b32 v253, s1, 1
	s_and_saveexec_b64 s[0:1], vcc
	v_lshl_add_u32 v1, v214, 2, 0
	v_add_u32_e32 v1, 0x21000, v1
	v_mov_b32_e32 v2, 0
	ds_write_b32 v1, v2
	s_or_b64 exec, exec, s[0:1]
	s_mov_b64 s[0:1], s[68:69]
	s_waitcnt lgkmcnt(0)
	s_barrier
	s_load_dwordx2 s[0:1], s[0:1], 0x90
	s_getreg_b32 s2, hwreg(HW_REG_XCC_ID, 0, 4)
	s_waitcnt lgkmcnt(0)
	s_add_u32 s0, s0, 0x8000
	s_addc_u32 s1, s1, 0
	v_writelane_b32 v253, s0, 2
	s_and_b32 s4, s2, 15
	v_cmp_eq_u32_e64 s[2:3], 0, v214
	v_writelane_b32 v253, s1, 3
	s_mov_b64 s[0:1], exec
	v_writelane_b32 v253, s2, 4
	s_nop 1
	v_writelane_b32 v253, s3, 5
	s_and_b64 s[2:3], s[0:1], s[2:3]
	s_mov_b64 exec, s[2:3]
	s_cbranch_execz .LBB0_5
	s_mov_b64 s[2:3], exec
	v_mbcnt_lo_u32_b32 v1, s2, 0
	v_mbcnt_hi_u32_b32 v1, s3, v1
	v_cmp_eq_u32_e32 vcc, 0, v1
	s_and_b64 s[6:7], exec, vcc
	s_mov_b64 exec, s[6:7]
	s_cbranch_execz .LBB0_5
	s_bcnt1_i32_b64 s2, s[2:3]
	s_lshl_b32 s5, s4, 8
	v_mov_b32_e32 v2, s2
	v_readlane_b32 s2, v253, 2
	v_mov_b32_e32 v1, s5
	v_readlane_b32 s3, v253, 3
	s_nop 4
	global_atomic_add v1, v2, s[2:3] offset:1024

; __device__ __forceinline__ int ltid() { int t = threadIdx.x; asm volatile("" : "+v"(t)); return t; }
; #define LAS __attribute__((address_space(3)))
; __global__ void __launch_bounds__(NWAVES * 64) fwd_kernel(Args args) {
;     ...
;         } else if (ph == 5 && PHON(5)) { TIDS;
;             char* L = (char*)lds; int* misc = (int*)(L + att::OFF_MISC); float* lut = (float*)(L + att::OFF_LUT);
;             const int home = (int)((unsigned)__builtin_amdgcn_s_getreg((3 << 11) | 20) & 7u);
;             const float lam = ((const float*)ctl)[CW_LAM];
;             for (int qq = 0; qq < 8; ++qq) { const int queue = (home + qq) & 7;
;                 for (;;) {
;                     __syncthreads();
;                     if (ltid() == 0) misc[0] = (int)atomicAdd(ctl + CW_CNT + 64 * (queue + 8 * (pi & 1)), 1u);
;                     __syncthreads();
;                     const int ui = misc[0]; if (ui >= QUNITS) break;
;     ...
;             { const int lane2 = ltid() & 63; LAS float* scr = (LAS float*)((LAS unsigned char*)lds + wave * 16640); int* misc2 = (int*)((char*)lds + att::OFF_MISC);
;               for (;;) {
;                   __syncthreads();
;                   if (ltid() == 0) misc2[0] = (int)atomicAdd(ctl + CW_TRC, 1u);
;                   __syncthreads();
;                   const int tu = misc2[0]; if (tu >= NTRU) break;
.Lbb32:
	v_mov_b32_e32 v0, v214
	s_getreg_b32 s1, hwreg(HW_REG_XCC_ID, 0, 4)
	v_readfirstlane_b32 s0, v0
	v_mov_b32_e32 v0, s16
	v_add_co_u32_e32 v2, vcc, 0x1000, v0
	v_mov_b32_e32 v0, s17
	s_nop 0
	v_addc_co_u32_e32 v3, vcc, 0, v0, vcc
	s_waitcnt vmcnt(0)
	flat_load_dword v221, v[2:3]
	v_writelane_b32 v254, s1, 36
	s_lshl_b32 s1, s72, 3
	s_ashr_i32 s2, s0, 6
	s_and_b32 s1, s1, 8
	v_writelane_b32 v254, s1, 37
	s_lshl_b32 s1, s2, 13
	s_add_i32 s1, s1, 0
	s_lshl_b32 s4, s2, 5
	s_add_i32 s1, s1, 0x11000
	v_writelane_b32 v254, s2, 38
	s_cmp_lt_u32 s0, 64
	v_writelane_b32 v254, s1, 39
	s_cselect_b64 s[0:1], -1, 0
	v_writelane_b32 v254, s0, 40
	s_mov_b32 s3, 0
	s_nop 0
	v_writelane_b32 v254, s1, 41
	s_add_u32 s0, s16, 0x10222000
	s_addc_u32 s1, s17, 0
	v_writelane_b32 v254, s0, 42
	s_nop 1
	v_writelane_b32 v254, s1, 43
	v_writelane_b32 v254, s4, 44
	s_sub_i32 s0, 0, s4
	v_writelane_b32 v254, s0, 45
	s_add_u32 s0, s16, 0x10220800
	s_addc_u32 s1, s17, 0
	v_writelane_b32 v254, s0, 46
	s_nop 1
	v_writelane_b32 v254, s1, 47
	s_mov_b64 s[0:1], s[72:73]
	s_mov_b32 s2, s74
	v_writelane_b32 v254, s0, 48
	s_nop 1
	v_writelane_b32 v254, s1, 49
	v_writelane_b32 v254, s2, 50
	v_writelane_b32 v254, s3, 51
	s_cmp_eq_u32 s98, 0
	s_cbranch_scc0 .Lgo_attn
	s_mov_b32 s98, 0x5a5a
	s_branch .LBB0_364
.Lgo_attn:
	s_branch .LBB0_34
.LBB0_33:
	v_readlane_b32 s3, v254, 52
	s_add_i32 s3, s3, 1
	s_cmp_eq_u32 s3, 8
	s_cbranch_scc1 .LBB0_364

; __device__ __forceinline__ int ltid() { int t = threadIdx.x; asm volatile("" : "+v"(t)); return t; }
; #define LAS __attribute__((address_space(3)))
; __device__ __forceinline__ KArgP kargs() { KArgP p = (KArgP)__builtin_amdgcn_kernarg_segment_ptr(); asm volatile("" : "+s"(p)); return p; }
; __global__ void __launch_bounds__(NWAVES * 64) fwd_kernel(Args args) {
;     ...
;             { const int lane2 = ltid() & 63; LAS float* scr = (LAS float*)((LAS unsigned char*)lds + wave * 16640); int* misc2 = (int*)((char*)lds + att::OFF_MISC);
;               for (;;) {
;                   __syncthreads();
;                   if (ltid() == 0) misc2[0] = (int)atomicAdd(ctl + CW_TRC, 1u);
;                   __syncthreads();
;                   const int tu = misc2[0]; if (tu >= NTRU) break;
;                   const int base = tu * 64 + wave * 8;
;                   for (int k = 0; k < 8; ++k) { int r = base + k; if (r >= NDEF) break;
;                       if (r < I_FI) { tr_item(kargs()->in[14], DM, 2 * DFF, WPTR(WS_W2IN), kargs()->in[13], 1, scr, r, lane2); continue; } r -= I_FI;
;                       if (r < I_FO) { tr_item(kargs()->in[15], DFF, DM, WPTR(WS_W2OUT), nullptr, 0, scr, r, lane2); continue; } r -= I_FO;
;                       tr_item(kargs()->in[12], DM, DM, WPTR(WS_WOUT), nullptr, 0, scr, r, lane2); } } }
.Ltr_exit:
	s_cmp_eq_u32 s98, 0x5a5a
	s_cbranch_scc0 .LBB0_407
	s_mov_b32 s98, 2
	s_branch .Lbb32
